# XCD-local seams: atomic-free arrival (per-workgroup flag words polled by one leader wave with a 64-lane sc1 load, release word polled by the rest); layout check also requires 8 distinct XCDs
# speedup vs baseline: 1.2557x; 1.0066x over previous
_Z14fwd_megakernel6Params:
	s_mov_b32 s100, 0
	v_writelane_b32 v255, s100, 56
	s_load_dwordx8 s[68:75], s[0:1], 0xc0
	s_add_u32 s8, s0, 0xe0
	v_and_b32_e32 v160, 0x3ff, v0
	s_addc_u32 s9, s1, 0
	s_mov_b32 s4, 0
	v_cmp_ne_u32_e32 vcc, 0, v160
	v_cmp_eq_u32_e64 s[14:15], 0, v160
	s_and_saveexec_b64 s[10:11], s[14:15]
	s_cbranch_execz .LBB0_2
	s_mov_b32 s5, s4
	s_mov_b32 s6, s4
	s_mov_b32 s7, s4
	v_mov_b64_e32 v[2:3], s[4:5]
	v_mov_b32_e32 v1, 0x13400
	v_mov_b64_e32 v[4:5], s[6:7]
	ds_write_b128 v1, v[2:5]
	v_mov_b32_e32 v1, 0x13410
	ds_write_b128 v1, v[2:5]

.LBB0_291:
	s_add_u32 s98, s74, 0x18934600
	s_addc_u32 s99, s75, 0
	v_and_b32_e32 v0, 7, v160
	v_lshlrev_b32_e32 v0, 2, v0
	global_load_dword v0, v0, s[98:99] sc1
	s_waitcnt vmcnt(0)
	v_readlane_b32 s100, v0, 0
	v_readlane_b32 s101, v0, 1
	s_or_b32 s100, s100, s101
	v_readlane_b32 s101, v0, 2
	s_or_b32 s100, s100, s101
	v_readlane_b32 s101, v0, 3
	s_or_b32 s100, s100, s101
	v_readlane_b32 s101, v0, 4
	s_or_b32 s100, s100, s101
	v_readlane_b32 s101, v0, 5
	s_or_b32 s100, s100, s101
	v_readlane_b32 s101, v0, 6
	s_or_b32 s100, s100, s101
	v_readlane_b32 s101, v0, 7
	s_or_b32 s100, s100, s101
	s_bcnt1_i32_b32 s100, s100
	v_bcnt_u32_b32 v0, v0, 0
	v_cmp_ne_u32_e32 vcc, 1, v0
	s_cmp_lg_u64 vcc, 0
	s_cselect_b32 s98, 1, 0
	s_cmp_lg_u32 s100, 8
	s_cselect_b32 s98, 1, s98
	v_writelane_b32 v255, s98, 63
	s_add_u32 s98, s74, 0x18936900
	s_addc_u32 s99, s75, 0
	s_lshl_b32 s100, s2, 2
	v_mov_b32_e32 v0, s100
	global_load_dword v0, v0, s[98:99] sc1
	s_waitcnt vmcnt(0)
	v_readfirstlane_b32 s100, v0
	s_add_u32 s98, s74, 0x18934680
	s_addc_u32 s99, s75, 0
	s_and_b32 s101, s2, 7
	s_lshl_b32 s101, s101, 2
	v_mov_b32_e32 v0, s101
	global_load_dword v0, v0, s[98:99] sc1
	s_waitcnt vmcnt(0)
	v_readfirstlane_b32 s98, v0
	s_lshr_b32 s99, s33, 3
	s_sub_u32 s99, 96, s99
	s_cmp_lt_i32 s98, s99
	s_cselect_b32 s100, -1, s100
	v_writelane_b32 v255, s100, 62
	s_and_b32 s48, s27, 3
	s_ashr_i32 s5, s2, 3
	s_ashr_i32 s33, s33, 3
	s_lshl_b32 s0, s76, 2
	s_add_u32 s0, s74, s0
	s_addc_u32 s1, s75, 0
	v_writelane_b32 v253, s27, 39
	s_add_u32 s0, s0, 0x1ad38500
	v_writelane_b32 v253, s0, 40
	s_addc_u32 s0, s1, 0
	v_writelane_b32 v253, s0, 41
	s_add_u32 s0, s74, 0x13800000
	s_addc_u32 s1, s75, 0
	v_writelane_b32 v253, s0, 42
	s_mul_i32 s94, s48, 6
	v_mov_b32_e32 v1, 0
	v_writelane_b32 v253, s1, 43
	s_lshl_b32 s0, s48, 6
	v_readlane_b32 s4, v253, 0
	s_lshl_b32 s1, s4, 3
	s_or_b32 s95, s1, 16
	s_lshl_b32 s96, s4, 4
	s_add_u32 s36, s74, 0x14400000
	s_addc_u32 s37, s75, 0
	s_add_u32 s66, s3, 0x4200
	s_addc_u32 s67, s86, 0
	s_add_u32 s80, s3, 0x4400
	s_addc_u32 s81, s86, 0
	s_add_u32 s82, s3, 0x4500
	s_addc_u32 s83, s86, 0
	s_add_u32 s6, s3, 0x4600
	v_writelane_b32 v253, s1, 44
	s_addc_u32 s7, s86, 0
	v_writelane_b32 v253, s6, 45
	s_mulk_i32 s48, 0x300
	v_mov_b32_e32 v161, 0x130b0
	v_writelane_b32 v253, s7, 46
	s_add_u32 s6, s3, 0x4700
	s_addc_u32 s7, s86, 0
	v_writelane_b32 v253, s6, 47
	v_mov_b32_e32 v201, 0x3727c5ac
	v_mbcnt_hi_u32_b32 v202, -1, v60
	v_writelane_b32 v253, s7, 48
	s_add_u32 s6, s3, 0x4800
	s_addc_u32 s7, s86, 0
	v_writelane_b32 v253, s6, 49
	v_mov_b32_e32 v205, 0xfffffc00
	v_mov_b32_e32 v206, 0xffffff00
	v_writelane_b32 v253, s7, 50
	s_add_u32 s6, s3, 0x4900
	s_addc_u32 s7, s86, 0
	v_writelane_b32 v253, s6, 51
	v_mov_b32_e32 v207, 0xe00
	v_mov_b32_e32 v208, 0xe40
	v_writelane_b32 v253, s7, 52
	s_add_u32 s6, s3, 0x4a00
	s_addc_u32 s7, s86, 0
	v_writelane_b32 v253, s6, 53
	v_mov_b32_e32 v209, 0xe60
	v_mov_b32_e32 v210, 0x200
	v_writelane_b32 v253, s7, 54
	s_add_u32 s6, s3, 0x4b00
	s_addc_u32 s7, s86, 0
	v_writelane_b32 v253, s6, 55
	v_mov_b32_e32 v211, 0xff800000
	v_mov_b32_e32 v212, 0xff61b1e6
	v_writelane_b32 v253, s7, 56
	s_add_u32 s6, s3, 0x4c00
	s_addc_u32 s7, s86, 0
	v_writelane_b32 v253, s6, 57
	s_movk_i32 s51, 0x300
	s_movk_i32 s52, 0x800
	v_writelane_b32 v253, s7, 58
	s_add_u32 s6, s3, 0x4d00
	s_addc_u32 s7, s86, 0
	v_writelane_b32 v253, s6, 59
	s_movk_i32 s53, 0x90
	s_mov_b32 s54, 0x10000
	v_writelane_b32 v253, s7, 60
	s_add_u32 s6, s3, 0x4e00
	s_addc_u32 s7, s86, 0
	v_writelane_b32 v253, s6, 61
	s_mov_b32 s55, 0x20000
	s_mov_b32 s56, 0x30000
	v_writelane_b32 v253, s7, 62
	s_add_u32 s6, s3, 0x4f00
	s_addc_u32 s7, s86, 0
	v_writelane_b32 v253, s6, 63
	s_movk_i32 s57, 0xfff
	s_movk_i32 s58, 0x1000
	v_writelane_b32 v254, s7, 0
	s_add_u32 s6, s3, 0x5000
	s_addc_u32 s7, s86, 0
	v_writelane_b32 v254, s6, 1
	s_movk_i32 s59, 0x110
	s_movk_i32 s60, 0x81
	v_writelane_b32 v254, s7, 2
	s_add_u32 s6, s3, 0x5100
	s_addc_u32 s7, s86, 0
	v_writelane_b32 v254, s6, 3
	s_mov_b32 s61, 0xff800000
	s_mov_b32 s62, 0x800000
	v_writelane_b32 v254, s7, 4
	s_add_u32 s6, s3, 0x5200
	s_addc_u32 s7, s86, 0
	s_add_u32 s84, s3, 0x5300
	v_writelane_b32 v254, s6, 5
	s_addc_u32 s85, s86, 0
	s_movk_i32 s63, 0x6000
	v_writelane_b32 v254, s7, 6
	s_add_u32 s6, s3, 0x7400
	s_addc_u32 s7, s86, 0
	v_writelane_b32 v254, s6, 7
	s_movk_i32 s64, 0x2ff
	s_movk_i32 s65, 0xff80
	v_writelane_b32 v254, s7, 8
	s_add_u32 s6, s3, 0x7500
	s_addc_u32 s7, s86, 0
	s_bfe_u32 s1, s2, 0x30001
	v_writelane_b32 v254, s6, 9
	s_lshl_b32 s2, s1, 6
	s_add_i32 s1, s87, s1
	v_writelane_b32 v254, s7, 10
	s_add_u32 s6, s74, 0x15c00000
	v_writelane_b32 v254, s1, 11
	s_addc_u32 s7, s75, 0
	v_writelane_b32 v254, s6, 12
	s_add_u32 s1, s74, 0x18688500
	s_mov_b64 s[88:89], 0x100
	v_writelane_b32 v254, s7, 13
	v_writelane_b32 v254, s1, 14
	s_addc_u32 s1, s75, 0
	v_writelane_b32 v254, s1, 15
	s_add_u32 s1, s74, 0x18788500
	v_writelane_b32 v254, s1, 16
	s_addc_u32 s1, s75, 0
	v_writelane_b32 v254, s1, 17
	s_add_u32 s1, s74, 0x18588500
	v_writelane_b32 v254, s1, 18
	s_addc_u32 s1, s75, 0
	v_writelane_b32 v254, s1, 19
	s_add_u32 s1, s74, 0x18608500
	v_writelane_b32 v254, s1, 20
	s_addc_u32 s1, s75, 0
	v_writelane_b32 v254, s1, 21
	s_add_u32 s1, s74, 0x18588000
	v_writelane_b32 v254, s1, 22
	s_addc_u32 s1, s75, 0
	v_writelane_b32 v254, s1, 23
	s_add_u32 s1, s74, 0x1000000
	v_writelane_b32 v254, s1, 24
	s_addc_u32 s1, s75, 0
	s_add_u32 s92, s74, 0x12000000
	s_addc_u32 s93, s75, 0
	s_add_u32 s6, s74, 0x18002000
	v_writelane_b32 v254, s1, 25
	s_addc_u32 s7, s75, 0
	v_writelane_b32 v254, s6, 26
	s_lshl_b32 s49, s4, 10
	s_lshl_b32 s1, s5, 2
	v_writelane_b32 v254, s7, 27
	v_writelane_b32 v254, s5, 28
	s_lshl_b32 s97, s33, 2
	s_bitset1_b32 s49, 11
	s_lshl_b32 s50, s4, 11
	v_writelane_b32 v254, s1, 29
	s_add_u32 s1, s74, 0x1800000
	v_writelane_b32 v254, s1, 30
	s_addc_u32 s1, s75, 0
	s_add_u32 s34, s74, 0x16800000
	s_addc_u32 s35, s75, 0
	s_add_u32 s4, s74, 0x18928700
	v_writelane_b32 v254, s1, 31
	s_addc_u32 s5, s75, 0
	v_writelane_b32 v254, s4, 32
	s_add_u32 s1, s74, 0x18908500
	s_mov_b64 s[22:23], 0
	v_writelane_b32 v254, s5, 33
	v_writelane_b32 v254, s1, 34
	s_addc_u32 s1, s75, 0
	v_writelane_b32 v254, s1, 35
	s_add_u32 s1, s74, 0x2000000
	v_writelane_b32 v254, s1, 36
	s_addc_u32 s1, s75, 0
	v_writelane_b32 v254, s1, 37
	s_add_u32 s1, s74, 0x18888500
	v_writelane_b32 v254, s1, 38
	s_addc_u32 s1, s75, 0
	v_writelane_b32 v254, s1, 39
	s_add_u32 s1, s74, 0x188c8500
	v_writelane_b32 v254, s1, 40
	s_addc_u32 s1, s75, 0
	s_add_u32 s8, s74, 0x30180
	s_addc_u32 s9, s75, 0
	s_add_u32 s10, s74, 0x10180
	s_addc_u32 s11, s75, 0
	s_add_u32 s12, s74, 0x180
	s_addc_u32 s13, s75, 0
	s_add_u32 s26, s74, 0x100
	s_addc_u32 s27, s75, 0
	s_add_u32 s28, s74, 0x10100
	s_addc_u32 s29, s75, 0
	s_add_u32 s30, s74, 0x20100
	v_writelane_b32 v254, s1, 41
	s_addc_u32 s31, s75, 0
	s_lshl_b32 s0, s0, 2
	v_writelane_b32 v254, s0, 42
	s_lshl_b32 s0, s2, 2
	s_mov_b64 s[4:5], s[72:73]
	v_writelane_b32 v254, s0, 43
	s_mov_b64 s[6:7], s[74:75]
	v_writelane_b32 v254, s0, 44
	s_mov_b32 s86, 0x3fd744fd
	s_mov_b32 s18, s21
	v_writelane_b32 v254, s1, 45
	v_writelane_b32 v254, s2, 46
	v_writelane_b32 v254, s3, 47
	v_writelane_b32 v254, s4, 48
	v_writelane_b32 v254, s5, 49
	v_writelane_b32 v254, s6, 50
	v_writelane_b32 v254, s7, 51
	v_writelane_b32 v254, s66, 52
	s_nop 1
	v_writelane_b32 v254, s67, 53
	v_writelane_b32 v254, s80, 54
	s_nop 1
	v_writelane_b32 v254, s81, 55
	v_writelane_b32 v254, s82, 56
	s_nop 1
	v_writelane_b32 v254, s83, 57
	v_writelane_b32 v254, s34, 58
	s_nop 1
	v_writelane_b32 v254, s35, 59
	s_branch .LBB0_295

.LBB0_642:
	s_getreg_b32 s4, hwreg(HW_REG_XCC_ID, 0, 4)
	s_waitcnt vmcnt(0)
	s_barrier
	s_and_saveexec_b64 s[2:3], s[14:15]
	s_cbranch_execz .LBB0_694
	v_readlane_b32 s98, v255, 63
	s_nop 0
	s_cmp_lg_u32 s98, 0
	s_cbranch_scc1 .Llb_full_g2
	s_cmp_lg_u32 s33, 64
	s_cbranch_scc1 .Llb_full_g2
	buffer_inv sc1
	v_readlane_b32 s98, v255, 56
	v_readlane_b32 s100, v253, 1
	v_readlane_b32 s101, v253, 2
	v_readlane_b32 s99, v253, 0
	v_readlane_b32 vcc_lo, v254, 28
	s_add_i32 s98, s98, 1
	v_writelane_b32 v255, s98, 56
	s_lshl_b32 s99, s99, 14
	s_sub_u32 s100, s100, s99
	s_subb_u32 s101, s101, 0
	s_add_u32 s100, s100, 0xb000
	s_addc_u32 s101, s101, 0
	s_getreg_b32 s99, hwreg(HW_REG_XCC_ID, 0, 4)
	s_and_b32 s99, s99, 15
	s_lshl_b32 s99, s99, 8
	s_lshl_b32 vcc_hi, vcc_lo, 2
	s_add_i32 vcc_hi, vcc_hi, s99
	v_mov_b32_e32 v4, vcc_hi
	v_mov_b32_e32 v5, s98
	global_store_dword v4, v5, s[100:101]
	s_cmp_eq_u32 vcc_lo, 0
	s_cbranch_scc1 .Llb_lead_g2
	s_lshr_b32 s99, s99, 2
	v_mov_b32_e32 v4, s99
	s_mov_b32 s99, 0
.Llb_fspin_g2:
	s_sleep 1
	global_load_dword v6, v4, s[100:101] offset:-1024 sc1
	s_add_i32 s99, s99, 1
	s_waitcnt vmcnt(0)
	v_readfirstlane_b32 vcc_lo, v6
	s_cmp_ge_u32 vcc_lo, s98
	s_cbranch_scc1 .Llb_done_g2
	s_cmp_lt_u32 s99, 0x2000
	s_cbranch_scc1 .Llb_fspin_g2
	s_branch .Llb_done_g2
.Llb_lead_g2:
	s_mov_b64 exec, -1
	v_mbcnt_lo_u32_b32 v4, -1, 0
	v_mbcnt_hi_u32_b32 v4, -1, v4
	v_lshl_add_u32 v4, v4, 2, s99
	v_mov_b32_e32 v5, 0
.Llb_lspin_g2:
	s_sleep 1
	global_load_dword v6, v4, s[100:101] sc1
	v_add_u32_e32 v5, 1, v5
	s_waitcnt vmcnt(0)
	v_cmp_gt_u32_e32 vcc, s98, v6
	s_cmp_eq_u64 vcc, 0
	s_cbranch_scc1 .Llb_lrel_g2
	v_readfirstlane_b32 vcc_lo, v5
	s_cmp_lt_u32 vcc_lo, 0x2000
	s_cbranch_scc1 .Llb_lspin_g2
.Llb_lrel_g2:
	s_mov_b64 exec, 1
	s_lshr_b32 s99, s99, 2
	v_mov_b32_e32 v4, s99
	v_mov_b32_e32 v5, s98
	global_store_dword v4, v5, s[100:101] offset:-1024
.Llb_done_g2:
	s_waitcnt vmcnt(0)
	s_branch .LBB0_694
.Llb_full_g2:
	v_mov_b32_e32 v0, 0x13410
	s_waitcnt vmcnt(0) expcnt(0) lgkmcnt(0)
	ds_read_b32 v3, v0
	v_mov_b32_e32 v0, 0x13414
	ds_read_b32 v2, v0
	s_and_b32 s10, s4, 15
	s_waitcnt lgkmcnt(1)
	v_cmp_ne_u32_e32 vcc, 0, v3
	s_cbranch_vccnz .LBB0_658
	s_mov_b32 s11, 1
	s_branch .LBB0_646

.LBB0_697:
	s_or_b64 exec, exec, s[2:3]
	s_getreg_b32 s4, hwreg(HW_REG_XCC_ID, 0, 4)
	s_waitcnt vmcnt(0)
	s_barrier
	s_and_saveexec_b64 s[2:3], s[14:15]
	s_cbranch_execz .LBB0_749
	v_readlane_b32 s98, v255, 63
	s_nop 0
	s_cmp_lg_u32 s98, 0
	s_cbranch_scc1 .Llb_full_ln1
	s_cmp_lg_u32 s33, 64
	s_cbranch_scc1 .Llb_full_ln1
	v_readlane_b32 s98, v255, 56
	v_readlane_b32 s100, v253, 1
	v_readlane_b32 s101, v253, 2
	v_readlane_b32 s99, v253, 0
	v_readlane_b32 vcc_lo, v254, 28
	s_add_i32 s98, s98, 1
	v_writelane_b32 v255, s98, 56
	s_lshl_b32 s99, s99, 14
	s_sub_u32 s100, s100, s99
	s_subb_u32 s101, s101, 0
	s_add_u32 s100, s100, 0xb000
	s_addc_u32 s101, s101, 0
	s_getreg_b32 s99, hwreg(HW_REG_XCC_ID, 0, 4)
	s_and_b32 s99, s99, 15
	s_lshl_b32 s99, s99, 8
	s_lshl_b32 vcc_hi, vcc_lo, 2
	s_add_i32 vcc_hi, vcc_hi, s99
	v_mov_b32_e32 v4, vcc_hi
	v_mov_b32_e32 v5, s98
	global_store_dword v4, v5, s[100:101]
	s_cmp_eq_u32 vcc_lo, 0
	s_cbranch_scc1 .Llb_lead_ln1
	s_lshr_b32 s99, s99, 2
	v_mov_b32_e32 v4, s99
	s_mov_b32 s99, 0

.LBB0_780:
	s_getreg_b32 s2, hwreg(HW_REG_XCC_ID, 0, 4)
	s_waitcnt vmcnt(0)
	s_barrier
	s_and_saveexec_b64 s[0:1], s[14:15]
	s_cbranch_execz .LBB0_832
	v_readlane_b32 s98, v255, 63
	s_nop 0
	s_cmp_lg_u32 s98, 0
	s_cbranch_scc1 .Llb_full_g3
	s_cmp_lg_u32 s33, 64
	s_cbranch_scc1 .Llb_full_g3
	buffer_inv sc1
	v_readlane_b32 s98, v255, 56
	v_readlane_b32 s100, v253, 1
	v_readlane_b32 s101, v253, 2
	v_readlane_b32 s99, v253, 0
	v_readlane_b32 vcc_lo, v254, 28
	s_add_i32 s98, s98, 1
	v_writelane_b32 v255, s98, 56
	s_lshl_b32 s99, s99, 14
	s_sub_u32 s100, s100, s99
	s_subb_u32 s101, s101, 0
	s_add_u32 s100, s100, 0xb000
	s_addc_u32 s101, s101, 0
	s_getreg_b32 s99, hwreg(HW_REG_XCC_ID, 0, 4)
	s_and_b32 s99, s99, 15
	s_lshl_b32 s99, s99, 8
	s_lshl_b32 vcc_hi, vcc_lo, 2
	s_add_i32 vcc_hi, vcc_hi, s99
	v_mov_b32_e32 v4, vcc_hi
	v_mov_b32_e32 v5, s98
	global_store_dword v4, v5, s[100:101]
	s_cmp_eq_u32 vcc_lo, 0
	s_cbranch_scc1 .Llb_lead_g3
	s_lshr_b32 s99, s99, 2
	v_mov_b32_e32 v4, s99
	s_mov_b32 s99, 0

.Llb_full_g3:
	v_mov_b32_e32 v0, 0x13410
	s_waitcnt vmcnt(0) expcnt(0) lgkmcnt(0)
	ds_read_b32 v3, v0
	v_mov_b32_e32 v0, 0x13414
	ds_read_b32 v2, v0
	s_and_b32 s8, s2, 15
	s_waitcnt lgkmcnt(1)
	v_cmp_ne_u32_e32 vcc, 0, v3
	s_cbranch_vccnz .LBB0_796
	s_mov_b32 s9, 1
	s_branch .LBB0_784

.LBB0_875:
	s_or_b64 exec, exec, s[44:45]
	s_setprio 0
	s_andn2_b64 vcc, exec, s[30:31]
	v_readlane_b32 s34, v254, 58
	v_readlane_b32 s35, v254, 59
	s_cbranch_vccnz .LBB0_294
	s_getreg_b32 s2, hwreg(HW_REG_XCC_ID, 0, 4)
	s_waitcnt vmcnt(0)
	s_waitcnt lgkmcnt(0)
	s_barrier
	s_and_saveexec_b64 s[0:1], s[14:15]
	s_cbranch_execz .LBB0_293
	v_readlane_b32 s98, v255, 63
	s_nop 0
	s_cmp_lg_u32 s98, 0
	s_cbranch_scc1 .Llb_full_peer
	s_cmp_lg_u32 s33, 64
	s_cbranch_scc1 .Llb_full_peer
	v_readlane_b32 s98, v255, 56
	v_readlane_b32 s100, v253, 1
	v_readlane_b32 s101, v253, 2
	v_readlane_b32 s99, v253, 0
	v_readlane_b32 vcc_lo, v254, 28
	s_add_i32 s98, s98, 1
	v_writelane_b32 v255, s98, 56
	s_lshl_b32 s99, s99, 14
	s_sub_u32 s100, s100, s99
	s_subb_u32 s101, s101, 0
	s_add_u32 s100, s100, 0xb000
	s_addc_u32 s101, s101, 0
	s_getreg_b32 s99, hwreg(HW_REG_XCC_ID, 0, 4)
	s_and_b32 s99, s99, 15
	s_lshl_b32 s99, s99, 8
	s_lshl_b32 vcc_hi, vcc_lo, 2
	s_add_i32 vcc_hi, vcc_hi, s99
	v_mov_b32_e32 v4, vcc_hi
	v_mov_b32_e32 v5, s98
	global_store_dword v4, v5, s[100:101]
	s_cmp_eq_u32 vcc_lo, 0
	s_cbranch_scc1 .Llb_lead_peer
	s_lshr_b32 s99, s99, 2
	v_mov_b32_e32 v4, s99
	s_mov_b32 s99, 0
